# P0 x->bf16 rows: second half of the row loads no longer waits for the first load's return (wait moved behind the issue of all eight loads)
# speedup vs baseline: 1.0025x; 1.0025x over previous
.LBB0_78:
	v_cmp_lt_i32_e32 vcc, s33, v0
	v_mov_b64_e32 v[10:11], v[0:1]
	v_mov_b64_e32 v[12:13], v[6:7]
	s_and_saveexec_b64 s[34:35], vcc
	v_add_u32_e32 v2, 0xffffe000, v0
	v_lshlrev_b64 v[10:11], 13, v[2:3]
	v_mov_b32_e32 v2, v0
	v_lshl_add_u64 v[12:13], s[14:15], 0, v[10:11]
	v_mov_b64_e32 v[10:11], v[2:3]
	s_or_b64 exec, exec, s[34:35]
	v_lshl_add_u64 v[12:13], v[12:13], 0, v[8:9]
	global_load_dwordx4 v[22:25], v[12:13], off nt
	global_load_dwordx4 v[26:29], v[12:13], off offset:1024 nt
	global_load_dwordx4 v[30:33], v[12:13], off offset:2048 nt
	global_load_dwordx4 v[34:37], v[12:13], off offset:3072 nt
	v_add_co_u32_e32 v12, vcc, s58, v12
	s_nop 1
	v_addc_co_u32_e32 v13, vcc, 0, v13, vcc
	global_load_dwordx4 v[38:41], v[12:13], off nt
	global_load_dwordx4 v[42:45], v[12:13], off offset:1024 nt
	global_load_dwordx4 v[46:49], v[12:13], off offset:3072 nt
	global_load_dwordx4 v[50:53], v[12:13], off offset:2048 nt
	s_waitcnt vmcnt(6)
	v_mov_b32_e32 v54, v23
	v_mov_b32_e32 v55, v27
	v_mov_b32_e32 v60, v25
	v_mov_b32_e32 v61, v29
	v_mov_b32_e32 v12, v22
	v_mov_b32_e32 v13, v26
	v_mov_b32_e32 v58, v24
	v_mov_b32_e32 v59, v28
	s_waitcnt vmcnt(5)
	v_pk_mul_f32 v[62:63], v[32:33], v[32:33]
	v_pk_mul_f32 v[64:65], v[30:31], v[30:31]
	v_pk_mul_f32 v[54:55], v[54:55], v[54:55]
	v_pk_mul_f32 v[60:61], v[60:61], v[60:61]
	v_pk_mov_b32 v[68:69], v[64:65], v[62:63] op_sel:[1,0]
	v_mov_b32_e32 v65, v63
	v_pk_fma_f32 v[12:13], v[12:13], v[12:13], v[54:55]
	v_pk_fma_f32 v[54:55], v[58:59], v[58:59], v[60:61]
	s_waitcnt vmcnt(4)
	v_mul_f32_e32 v2, v35, v35
	v_mul_f32_e32 v66, v37, v37
	v_pk_add_f32 v[58:59], v[68:69], v[64:65]
	v_pk_add_f32 v[12:13], v[12:13], v[54:55]
	v_pk_fma_f32 v[62:63], v[34:35], v[34:35], v[2:3] op_sel_hi:[1,1,0]
	v_pk_fma_f32 v[66:67], v[36:37], v[36:37], v[66:67] op_sel_hi:[1,1,0]
	v_pk_add_f32 v[54:55], v[58:59], v[58:59] op_sel:[0,1] op_sel_hi:[1,0]
	v_pk_add_f32 v[12:13], v[12:13], v[12:13] op_sel:[0,1] op_sel_hi:[1,0]
	s_waitcnt vmcnt(3)
	v_mul_f32_e32 v21, v38, v38
	v_mul_f32_e32 v57, v39, v39
	v_mul_f32_e32 v75, v40, v40
	v_mul_f32_e32 v76, v41, v41
	s_waitcnt vmcnt(2)
	v_pk_mul_f32 v[70:71], v[44:45], v[44:45]
	v_pk_mul_f32 v[72:73], v[42:43], v[42:43]
	v_mov_b32_e32 v63, v75
	v_mov_b32_e32 v67, v76
	v_mov_b32_e32 v55, v57
	v_mov_b32_e32 v13, v21
	v_pk_mov_b32 v[60:61], v[72:73], v[70:71] op_sel:[1,0]
	v_mov_b32_e32 v73, v71
	v_pk_add_f32 v[58:59], v[62:63], v[66:67]
	v_pk_add_f32 v[12:13], v[12:13], v[54:55]
	s_waitcnt vmcnt(0)
	v_mul_f32_e32 v2, v51, v51
	v_mul_f32_e32 v74, v53, v53
	v_pk_add_f32 v[60:61], v[60:61], v[72:73]
	v_pk_add_f32 v[12:13], v[12:13], v[58:59]
	v_mul_f32_e32 v77, v46, v46
	v_mul_f32_e32 v78, v47, v47
	v_mul_f32_e32 v79, v48, v48
	v_mul_f32_e32 v80, v49, v49
	v_pk_fma_f32 v[64:65], v[50:51], v[50:51], v[2:3] op_sel_hi:[1,1,0]
	v_pk_fma_f32 v[68:69], v[52:53], v[52:53], v[74:75] op_sel_hi:[1,1,0]
	v_pk_add_f32 v[60:61], v[60:61], v[60:61] op_sel:[0,1] op_sel_hi:[1,0]
	v_pk_add_f32 v[12:13], v[12:13], v[12:13] op_sel:[0,1] op_sel_hi:[1,0]
	v_mov_b32_e32 v65, v79
	v_mov_b32_e32 v69, v80
	v_mov_b32_e32 v61, v78
	v_mov_b32_e32 v13, v77
	v_pk_add_f32 v[62:63], v[64:65], v[68:69]
	v_pk_add_f32 v[12:13], v[12:13], v[60:61]
	s_nop 0
	v_pk_add_f32 v[12:13], v[12:13], v[62:63]
	s_nop 0
	v_add_f32_e32 v2, v12, v13
	ds_bpermute_b32 v12, v14, v2
	s_waitcnt lgkmcnt(0)
	v_add_f32_e32 v2, v2, v12
	ds_bpermute_b32 v12, v15, v2
	s_waitcnt lgkmcnt(0)
	v_add_f32_e32 v2, v2, v12
	ds_bpermute_b32 v12, v16, v2
	s_waitcnt lgkmcnt(0)
	v_add_f32_e32 v2, v2, v12
	ds_bpermute_b32 v12, v17, v2
	s_waitcnt lgkmcnt(0)
	v_add_f32_e32 v2, v2, v12
	ds_bpermute_b32 v12, v18, v2
	s_waitcnt lgkmcnt(0)
	v_add_f32_e32 v2, v2, v12
	ds_bpermute_b32 v12, v19, v2
	s_waitcnt lgkmcnt(0)
	v_add_f32_e32 v2, v2, v12
	v_fmamk_f32 v2, v2, 0x3a000000, v20
	v_mul_f32_e32 v12, 0x4b800000, v2
	v_cmp_gt_f32_e32 vcc, s59, v2
	s_nop 1
	v_cndmask_b32_e32 v2, v2, v12, vcc
	v_rsq_f32_e32 v2, v2
	v_lshlrev_b64 v[12:13], 12, v[10:11]
	v_lshl_add_u64 v[12:13], v[4:5], 0, v[12:13]
	v_mul_f32_e32 v21, 0x45800000, v2
	v_cndmask_b32_e32 v2, v2, v21, vcc
	v_mul_f32_e32 v21, v22, v2
	v_mul_f32_e32 v22, v23, v2
	v_mul_f32_e32 v23, v24, v2
	v_mul_f32_e32 v24, v25, v2
	v_mul_f32_e32 v25, v26, v2
	v_mul_f32_e32 v26, v27, v2
	v_mul_f32_e32 v27, v28, v2
	v_mul_f32_e32 v28, v29, v2
	v_mul_f32_e32 v29, v30, v2
	v_mul_f32_e32 v30, v31, v2
	v_mul_f32_e32 v31, v32, v2
	v_mul_f32_e32 v32, v33, v2
	v_mul_f32_e32 v33, v34, v2
	v_mul_f32_e32 v34, v35, v2
	v_mul_f32_e32 v35, v36, v2
	v_cvt_pk_bf16_f32 v22, v21, v22
	v_cvt_pk_bf16_f32 v23, v23, v24
	v_mul_f32_e32 v36, v37, v2
	v_mul_f32_e32 v37, v38, v2
	v_mul_f32_e32 v38, v39, v2
	v_mul_f32_e32 v39, v40, v2
	v_mul_f32_e32 v40, v41, v2
	v_mul_f32_e32 v41, v42, v2
	v_mul_f32_e32 v42, v43, v2
	v_mul_f32_e32 v43, v44, v2
	v_mul_f32_e32 v44, v45, v2
	v_mul_f32_e32 v45, v50, v2
	v_mul_f32_e32 v50, v51, v2
	v_mul_f32_e32 v51, v52, v2
	v_mul_f32_e32 v52, v53, v2
	v_cvt_pk_bf16_f32 v24, v25, v26
	v_cvt_pk_bf16_f32 v25, v27, v28
	v_cvt_pk_bf16_f32 v26, v29, v30
	v_cvt_pk_bf16_f32 v27, v31, v32
	v_cvt_pk_bf16_f32 v28, v33, v34
	v_cvt_pk_bf16_f32 v29, v35, v36
	v_cvt_pk_bf16_f32 v30, v37, v38
	v_cvt_pk_bf16_f32 v31, v39, v40
	v_cvt_pk_bf16_f32 v32, v41, v42
	v_cvt_pk_bf16_f32 v33, v43, v44
	v_cvt_pk_bf16_f32 v34, v45, v50
	v_cvt_pk_bf16_f32 v35, v51, v52
	global_store_dwordx2 v[12:13], v[22:23], off
	global_store_dwordx2 v[12:13], v[24:25], off offset:512
	global_store_dwordx2 v[12:13], v[26:27], off offset:1024
	global_store_dwordx2 v[12:13], v[28:29], off offset:1536
	global_store_dwordx2 v[12:13], v[30:31], off offset:2048
	global_store_dwordx2 v[12:13], v[32:33], off offset:2560
	global_store_dwordx2 v[12:13], v[34:35], off offset:3072
	v_mul_f32_e32 v21, v47, v2
	v_mul_f32_e32 v23, v49, v2
	v_mul_f32_e32 v46, v46, v2
	v_cvt_pk_bf16_f32 v22, v46, v21
	v_mul_f32_e32 v21, v48, v2
	v_cvt_pk_bf16_f32 v23, v21, v23
	global_store_dwordx2 v[12:13], v[22:23], off offset:3584
	s_and_saveexec_b64 s[34:35], s[0:1]
	s_cbranch_execz .LBB0_77
	v_lshl_add_u64 v[10:11], v[10:11], 2, s[6:7]
	global_store_dword v[10:11], v2, off
	s_branch .LBB0_77
